# P1: derived per-channel vectors computed by four workgroups (one 512-slice each) instead of serially by workgroup 0; stacked on all previous changes
# speedup vs baseline: 1.0076x; 1.0076x over previous
.LBB0_49:
	v_readlane_b32 s0, v254, 5
	v_readlane_b32 s1, v254, 6
	s_cmp_lt_i32 s0, 2
	s_cselect_b64 s[0:1], -1, 0
	s_and_b64 s[6:7], s[0:1], s[6:7]
	s_andn2_b64 vcc, exec, s[6:7]
	s_cbranch_vccnz .LBB0_57
	v_readlane_b32 s0, v254, 2
	s_cmp_gt_u32 s0, 3
	s_cbranch_scc0 .LBB0_52
	s_cmpk_gt_i32 s76, 0x1fff
	s_cbranch_scc0 .LBB0_55
	s_branch .LBB0_57
.LBB0_52:
	s_waitcnt vmcnt(34)
	v_mov_b32_e32 v1, 0x600
	v_lshlrev_b32_e32 v2, 2, v0
	s_waitcnt vmcnt(32)
	v_mov_b32_e32 v3, 0
	s_mov_b64 s[8:9], 0
	s_movk_i32 s28, 0x5ff
	s_mov_b64 s[10:11], s[26:27]
	v_readlane_b32 s0, v254, 2
	s_lshl_b32 s0, s0, 11
	s_add_u32 s10, s10, s0
	s_addc_u32 s11, s11, 0
	s_add_u32 s46, s46, s0
	s_addc_u32 s47, s47, 0
	s_add_u32 s12, s12, s0
	s_addc_u32 s13, s13, 0
	s_add_u32 s14, s14, s0
	s_addc_u32 s15, s15, 0
